# phase 0 modulation tiles: the twelve condition loads of the silu prologue issued together instead of one per wait
# baseline (speedup 1.0000x reference)
.LBB0_1343:
	s_andn2_b64 vcc, exec, s[34:35]
	s_cbranch_vccnz .LBB0_1361
	s_waitcnt vmcnt(2)
	v_mov_b32_e32 v20, v170
	s_movk_i32 s34, 0xbff
	s_waitcnt lgkmcnt(0)
	v_cmp_lt_i32_e32 vcc, s34, v20
	v_lshlrev_b32_e32 v2, 2, v20
	s_barrier
	s_and_saveexec_b64 s[34:35], vcc
	s_xor_b64 s[34:35], exec, s[34:35]
	v_lshlrev_b32_e32 v2, 2, v20
	s_andn2_saveexec_b64 s[34:35], s[34:35]
	s_cbranch_execz .LBB0_1355
	s_mov_b64 s[36:37], 0
	v_mov_b32_e32 v3, v2
	v_mov_b32_e32 v4, v20
	v_readlane_b32 s4, v237, 19
	v_readlane_b32 s5, v237, 20
	v_readlane_b32 s6, v237, 17
	v_readlane_b32 s7, v237, 18
	s_add_u32 s8, s6, 0x1000
	s_addc_u32 s9, s7, 0
	s_nop 4
	global_load_dword v44, v2, s[4:5]
	global_load_dword v45, v2, s[4:5] offset:1024
	global_load_dword v46, v2, s[4:5] offset:2048
	global_load_dword v47, v2, s[4:5] offset:3072
	global_load_dword v48, v2, s[6:7]
	global_load_dword v49, v2, s[6:7] offset:1024
	global_load_dword v50, v2, s[6:7] offset:2048
	global_load_dword v51, v2, s[6:7] offset:3072
	global_load_dword v52, v2, s[8:9]
	global_load_dword v53, v2, s[8:9] offset:1024
	global_load_dword v54, v2, s[8:9] offset:2048
	global_load_dword v55, v2, s[8:9] offset:3072
	s_waitcnt vmcnt(11)
	v_mul_f32_e32 v24, 0xbfb8aa3b, v44
	v_exp_f32_e32 v24, v24
	s_nop 0
	v_add_f32_e32 v24, 1.0, v24
	v_div_scale_f32 v25, s[40:41], v24, v24, v44
	v_rcp_f32_e32 v26, v25
	s_nop 0
	v_fma_f32 v27, -v25, v26, 1.0
	v_fmac_f32_e32 v26, v27, v26
	v_div_scale_f32 v27, vcc, v44, v24, v44
	v_mul_f32_e32 v28, v27, v26
	v_fma_f32 v29, -v25, v28, v27
	v_fmac_f32_e32 v28, v29, v26
	v_fma_f32 v25, -v25, v28, v27
	v_div_fmas_f32 v25, v25, v26, v28
	v_div_fixup_f32 v30, v25, v24, v44
	ds_write_b32 v2, v30
	s_waitcnt vmcnt(10)
	v_mul_f32_e32 v24, 0xbfb8aa3b, v45
	v_exp_f32_e32 v24, v24
	s_nop 0
	v_add_f32_e32 v24, 1.0, v24
	v_div_scale_f32 v25, s[40:41], v24, v24, v45
	v_rcp_f32_e32 v26, v25
	s_nop 0
	v_fma_f32 v27, -v25, v26, 1.0
	v_fmac_f32_e32 v26, v27, v26
	v_div_scale_f32 v27, vcc, v45, v24, v45
	v_mul_f32_e32 v28, v27, v26
	v_fma_f32 v29, -v25, v28, v27
	v_fmac_f32_e32 v28, v29, v26
	v_fma_f32 v25, -v25, v28, v27
	v_div_fmas_f32 v25, v25, v26, v28
	v_div_fixup_f32 v30, v25, v24, v45
	ds_write_b32 v2, v30 offset:1024
	s_waitcnt vmcnt(9)
	v_mul_f32_e32 v24, 0xbfb8aa3b, v46
	v_exp_f32_e32 v24, v24
	s_nop 0
	v_add_f32_e32 v24, 1.0, v24
	v_div_scale_f32 v25, s[40:41], v24, v24, v46
	v_rcp_f32_e32 v26, v25
	s_nop 0
	v_fma_f32 v27, -v25, v26, 1.0
	v_fmac_f32_e32 v26, v27, v26
	v_div_scale_f32 v27, vcc, v46, v24, v46
	v_mul_f32_e32 v28, v27, v26
	v_fma_f32 v29, -v25, v28, v27
	v_fmac_f32_e32 v28, v29, v26
	v_fma_f32 v25, -v25, v28, v27
	v_div_fmas_f32 v25, v25, v26, v28
	v_div_fixup_f32 v30, v25, v24, v46
	ds_write_b32 v2, v30 offset:2048
	s_waitcnt vmcnt(8)
	v_mul_f32_e32 v24, 0xbfb8aa3b, v47
	v_exp_f32_e32 v24, v24
	s_nop 0
	v_add_f32_e32 v24, 1.0, v24
	v_div_scale_f32 v25, s[40:41], v24, v24, v47
	v_rcp_f32_e32 v26, v25
	s_nop 0
	v_fma_f32 v27, -v25, v26, 1.0
	v_fmac_f32_e32 v26, v27, v26
	v_div_scale_f32 v27, vcc, v47, v24, v47
	v_mul_f32_e32 v28, v27, v26
	v_fma_f32 v29, -v25, v28, v27
	v_fmac_f32_e32 v28, v29, v26
	v_fma_f32 v25, -v25, v28, v27
	v_div_fmas_f32 v25, v25, v26, v28
	v_div_fixup_f32 v30, v25, v24, v47
	ds_write_b32 v2, v30 offset:3072
	s_waitcnt vmcnt(7)
	v_mul_f32_e32 v24, 0xbfb8aa3b, v48
	v_exp_f32_e32 v24, v24
	s_nop 0
	v_add_f32_e32 v24, 1.0, v24
	v_div_scale_f32 v25, s[40:41], v24, v24, v48
	v_rcp_f32_e32 v26, v25
	s_nop 0
	v_fma_f32 v27, -v25, v26, 1.0
	v_fmac_f32_e32 v26, v27, v26
	v_div_scale_f32 v27, vcc, v48, v24, v48
	v_mul_f32_e32 v28, v27, v26
	v_fma_f32 v29, -v25, v28, v27
	v_fmac_f32_e32 v28, v29, v26
	v_fma_f32 v25, -v25, v28, v27
	v_div_fmas_f32 v25, v25, v26, v28
	v_div_fixup_f32 v30, v25, v24, v48
	ds_write_b32 v2, v30 offset:4096
	s_waitcnt vmcnt(6)
	v_mul_f32_e32 v24, 0xbfb8aa3b, v49
	v_exp_f32_e32 v24, v24
	s_nop 0
	v_add_f32_e32 v24, 1.0, v24
	v_div_scale_f32 v25, s[40:41], v24, v24, v49
	v_rcp_f32_e32 v26, v25
	s_nop 0
	v_fma_f32 v27, -v25, v26, 1.0
	v_fmac_f32_e32 v26, v27, v26
	v_div_scale_f32 v27, vcc, v49, v24, v49
	v_mul_f32_e32 v28, v27, v26
	v_fma_f32 v29, -v25, v28, v27
	v_fmac_f32_e32 v28, v29, v26
	v_fma_f32 v25, -v25, v28, v27
	v_div_fmas_f32 v25, v25, v26, v28
	v_div_fixup_f32 v30, v25, v24, v49
	ds_write_b32 v2, v30 offset:5120
	s_waitcnt vmcnt(5)
	v_mul_f32_e32 v24, 0xbfb8aa3b, v50
	v_exp_f32_e32 v24, v24
	s_nop 0
	v_add_f32_e32 v24, 1.0, v24
	v_div_scale_f32 v25, s[40:41], v24, v24, v50
	v_rcp_f32_e32 v26, v25
	s_nop 0
	v_fma_f32 v27, -v25, v26, 1.0
	v_fmac_f32_e32 v26, v27, v26
	v_div_scale_f32 v27, vcc, v50, v24, v50
	v_mul_f32_e32 v28, v27, v26
	v_fma_f32 v29, -v25, v28, v27
	v_fmac_f32_e32 v28, v29, v26
	v_fma_f32 v25, -v25, v28, v27
	v_div_fmas_f32 v25, v25, v26, v28
	v_div_fixup_f32 v30, v25, v24, v50
	ds_write_b32 v2, v30 offset:6144
	s_waitcnt vmcnt(4)
	v_mul_f32_e32 v24, 0xbfb8aa3b, v51
	v_exp_f32_e32 v24, v24
	s_nop 0
	v_add_f32_e32 v24, 1.0, v24
	v_div_scale_f32 v25, s[40:41], v24, v24, v51
	v_rcp_f32_e32 v26, v25
	s_nop 0
	v_fma_f32 v27, -v25, v26, 1.0
	v_fmac_f32_e32 v26, v27, v26
	v_div_scale_f32 v27, vcc, v51, v24, v51
	v_mul_f32_e32 v28, v27, v26
	v_fma_f32 v29, -v25, v28, v27
	v_fmac_f32_e32 v28, v29, v26
	v_fma_f32 v25, -v25, v28, v27
	v_div_fmas_f32 v25, v25, v26, v28
	v_div_fixup_f32 v30, v25, v24, v51
	ds_write_b32 v2, v30 offset:7168
	s_waitcnt vmcnt(3)
	v_mul_f32_e32 v24, 0xbfb8aa3b, v52
	v_exp_f32_e32 v24, v24
	s_nop 0
	v_add_f32_e32 v24, 1.0, v24
	v_div_scale_f32 v25, s[40:41], v24, v24, v52
	v_rcp_f32_e32 v26, v25
	s_nop 0
	v_fma_f32 v27, -v25, v26, 1.0
	v_fmac_f32_e32 v26, v27, v26
	v_div_scale_f32 v27, vcc, v52, v24, v52
	v_mul_f32_e32 v28, v27, v26
	v_fma_f32 v29, -v25, v28, v27
	v_fmac_f32_e32 v28, v29, v26
	v_fma_f32 v25, -v25, v28, v27
	v_div_fmas_f32 v25, v25, v26, v28
	v_div_fixup_f32 v30, v25, v24, v52
	ds_write_b32 v2, v30 offset:8192
	s_waitcnt vmcnt(2)
	v_mul_f32_e32 v24, 0xbfb8aa3b, v53
	v_exp_f32_e32 v24, v24
	s_nop 0
	v_add_f32_e32 v24, 1.0, v24
	v_div_scale_f32 v25, s[40:41], v24, v24, v53
	v_rcp_f32_e32 v26, v25
	s_nop 0
	v_fma_f32 v27, -v25, v26, 1.0
	v_fmac_f32_e32 v26, v27, v26
	v_div_scale_f32 v27, vcc, v53, v24, v53
	v_mul_f32_e32 v28, v27, v26
	v_fma_f32 v29, -v25, v28, v27
	v_fmac_f32_e32 v28, v29, v26
	v_fma_f32 v25, -v25, v28, v27
	v_div_fmas_f32 v25, v25, v26, v28
	v_div_fixup_f32 v30, v25, v24, v53
	ds_write_b32 v2, v30 offset:9216
	s_waitcnt vmcnt(1)
	v_mul_f32_e32 v24, 0xbfb8aa3b, v54
	v_exp_f32_e32 v24, v24
	s_nop 0
	v_add_f32_e32 v24, 1.0, v24
	v_div_scale_f32 v25, s[40:41], v24, v24, v54
	v_rcp_f32_e32 v26, v25
	s_nop 0
	v_fma_f32 v27, -v25, v26, 1.0
	v_fmac_f32_e32 v26, v27, v26
	v_div_scale_f32 v27, vcc, v54, v24, v54
	v_mul_f32_e32 v28, v27, v26
	v_fma_f32 v29, -v25, v28, v27
	v_fmac_f32_e32 v28, v29, v26
	v_fma_f32 v25, -v25, v28, v27
	v_div_fmas_f32 v25, v25, v26, v28
	v_div_fixup_f32 v30, v25, v24, v54
	ds_write_b32 v2, v30 offset:10240
	s_waitcnt vmcnt(0)
	v_mul_f32_e32 v24, 0xbfb8aa3b, v55
	v_exp_f32_e32 v24, v24
	s_nop 0
	v_add_f32_e32 v24, 1.0, v24
	v_div_scale_f32 v25, s[40:41], v24, v24, v55
	v_rcp_f32_e32 v26, v25
	s_nop 0
	v_fma_f32 v27, -v25, v26, 1.0
	v_fmac_f32_e32 v26, v27, v26
	v_div_scale_f32 v27, vcc, v55, v24, v55
	v_mul_f32_e32 v28, v27, v26
	v_fma_f32 v29, -v25, v28, v27
	v_fmac_f32_e32 v28, v29, v26
	v_fma_f32 v25, -v25, v28, v27
	v_div_fmas_f32 v25, v25, v26, v28
	v_div_fixup_f32 v30, v25, v24, v55
	ds_write_b32 v2, v30 offset:11264
	s_branch .LBB0_1355
